# attention loop: row-sum as packed tree adds under the last PV MFMAs, dropped accumulator copies; plus v15 changes
# speedup vs baseline: 1.0067x; 1.0067x over previous
; #define LAS __attribute__((address_space(3)))
; template <bool NA> ...
;     ...
;             float ls = 0.f;
; #pragma unroll
;             for (int r = 0; r < 16; ++r) { p0[r] = __builtin_amdgcn_exp2f(p0[r]); p1[r] = __builtin_amdgcn_exp2f(p1[r]); ls += p0[r] + p1[r]; }
;             l += ls;
;     ...
;         if (j + 1 < ntiles) {
;             *(LAS u32x4*)(lds + (cur ^ 1) * KB + srow * 144 + sch * 16) = kreg;
;             LAS unsigned char* vp = lds + VOFF + (cur ^ 1) * VB + srow * 144 + (sch >> 1) * 32 + (sch & 1) * 8;
;             *(LAS u32x2*)vp = (u32x2){vreg.x, vreg.y}; *(LAS u32x2*)(vp + 16) = (u32x2){vreg.z, vreg.w};
;         }
;         __syncthreads();
.LBB0_304:
	s_add_i32 s2, s2, 1
	s_mov_b64 s[22:23], 0xd8000
	v_add_f32_e32 v142, v142, v50
	v_lshl_add_u64 v[138:139], v[138:139], 0, s[22:23]
	s_cmpk_lg_i32 s2, 0x104
	v_lshl_add_u64 v[140:141], v[140:141], 0, s[10:11]
	s_waitcnt lgkmcnt(0)
	s_barrier
	s_cbranch_scc0 .LBB0_294

; template <bool NA> ...
;     ...
;         bool active = true; int kr = 0;
;         if (NA && j >= 4) { kr = na_rs_base + (j - 4); active = (kr >= na_rs) && (kr < na_rs + 8); }
;         if (active) {
;             const LAS unsigned char* kb = lds + cur * KB; const LAS unsigned char* vb = lds + VOFF + cur * VB;
;             f32x16 p0, p1;
;             if (NA) {
; #pragma unroll
;                 for (int r = 0; r < 16; ++r) { p0[r] = 0.f; p1[r] = 0.f; }
;             } else { p0 = negm; p1 = negm; }
;             bf16x8 kf[8], vfr[8];
; #pragma unroll
;             for (int s = 0; s < 4; ++s) {
;                 kf[2 * s] = *(const LAS bf16x8*)(kb + q * 144 + (16 * s + 8 * h) * 2);
;                 kf[2 * s + 1] = *(const LAS bf16x8*)(kb + (q + 32) * 144 + (16 * s + 8 * h) * 2);
;             }
; #pragma unroll
;             for (int s = 0; s < 4; ++s) {
;                 vfr[2 * s] = *(const LAS bf16x8*)(vb + q * 144 + 32 * s + 16 * h);
;                 vfr[2 * s + 1] = *(const LAS bf16x8*)(vb + (q + 32) * 144 + 32 * s + 16 * h);
;             }
;             __builtin_amdgcn_sched_barrier(0);
;             __builtin_amdgcn_s_setprio(1);
; #pragma unroll
;             for (int s = 0; s < 4; ++s) {
;                 p0 = __builtin_amdgcn_mfma_f32_32x32x16_bf16(kf[2 * s], qb[s], p0, 0, 0, 0);
;                 p1 = __builtin_amdgcn_mfma_f32_32x32x16_bf16(kf[2 * s + 1], qb[s], p1, 0, 0, 0);
;             }
;             __builtin_amdgcn_s_setprio(0);
;             if (NA) {
;                 if (j >= 4) {
;                     const int dr = kr - na_r + 7, qc = na_qc0 + q;
; #pragma unroll
;                     for (int r = 0; r < 16; ++r) {
;                         const int kc = 8 * (r >> 2) + 4 * h + (r & 3);
;                         const bool v0 = (kc >= na_cs) && (kc < na_cs + 16), v1 = (kc + 32 >= na_cs) && (kc + 32 < na_cs + 16);
;                         const int i0 = v0 ? dr * 31 + (kc - qc + 15) : 0, i1 = v1 ? dr * 31 + (kc + 32 - qc + 15) : 0;
;                         const float b0 = biasL[i0], b1 = biasL[i1];
;                         p0[r] = v0 ? p0[r] * qs + b0 - m : -INFINITY; p1[r] = v1 ? p1[r] * qs + b1 - m : -INFINITY;
;                     }
;                 } else {
; #pragma unroll
;                     for (int r = 0; r < 16; ++r) { p0[r] = p0[r] * qs - m; p1[r] = p1[r] * qs - m; }
;                 }
;             }
.LBB0_307:
	s_and_b32 s20, s2, 1
	s_mul_i32 s22, s20, 0x2400
	v_add_u32_e32 v50, s22, v194
	ds_read_b128 v[66:69], v50
	ds_read_b128 v[144:147], v50 offset:32
	ds_read_b128 v[148:151], v50 offset:4608
	ds_read_b128 v[188:191], v50 offset:4640
	ds_read_b128 v[196:199], v50 offset:64
	ds_read_b128 v[218:221], v50 offset:96
	ds_read_b128 v[222:225], v50 offset:4672
	ds_read_b128 v[226:229], v50 offset:4704
	ds_read_b128 v[134:137], v50 offset:18432
	ds_read_b128 v[126:129], v50 offset:18464
	ds_read_b128 v[130:133], v50 offset:23040
	ds_read_b128 v[122:125], v50 offset:23072
	ds_read_b128 v[118:121], v50 offset:18496
	ds_read_b128 v[90:93], v50 offset:18528
	ds_read_b128 v[114:117], v50 offset:23104
	ds_read_b128 v[94:97], v50 offset:23136
	s_setprio 1
	s_waitcnt lgkmcnt(14)
	v_mfma_f32_32x32x16_bf16 v[50:65], v[66:69], v[98:101], v[2:17]
	v_mfma_f32_32x32x16_bf16 v[50:65], v[144:147], v[102:105], v[50:65]
	s_waitcnt lgkmcnt(13)
	v_mfma_f32_32x32x16_bf16 v[66:81], v[148:151], v[98:101], v[2:17]
	s_waitcnt lgkmcnt(12)
	v_mfma_f32_32x32x16_bf16 v[66:81], v[188:191], v[102:105], v[66:81]
	s_waitcnt lgkmcnt(11)
	v_mfma_f32_32x32x16_bf16 v[50:65], v[196:199], v[106:109], v[50:65]
	s_waitcnt lgkmcnt(9)
	v_mfma_f32_32x32x16_bf16 v[66:81], v[222:225], v[106:109], v[66:81]
	v_mfma_f32_32x32x16_bf16 v[50:65], v[218:221], v[110:113], v[50:65]
	s_waitcnt lgkmcnt(8)
	v_mfma_f32_32x32x16_bf16 v[66:81], v[226:229], v[110:113], v[66:81]
	s_setprio 0
	s_nop 10
	v_max3_f32 v143, v50, v66, v51
	v_max3_f32 v143, v143, v53, v69
	v_max3_f32 v143, v143, v55, v71
	v_max3_f32 v143, v143, v56, v72
	v_max3_f32 v144, v67, v52, v68
	v_max3_f32 v143, v143, v58, v74
	v_max3_f32 v144, v144, v54, v70
	v_max3_f32 v143, v143, v59, v75
	v_max3_f32 v144, v144, v57, v73
	v_max3_f32 v143, v143, v61, v77
	v_max3_f32 v144, v144, v60, v76
	v_max3_f32 v143, v143, v62, v78
	v_max_f32_e32 v145, v81, v81
	v_max_f32_e32 v146, v65, v65
	v_max3_f32 v144, v144, v63, v79
	v_max3_f32 v143, v143, v64, v80
	v_max_f32_e32 v145, v146, v145
	v_max3_f32 v143, v143, v144, v145
	v_mov_b32_e32 v144, v143
	s_nop 1
	v_permlane32_swap_b32_e32 v143, v144
	v_max_f32_e32 v144, v144, v144
	v_max_f32_e32 v143, v143, v143
	v_max_f32_e32 v143, v143, v144
	v_cmp_lt_f32_e32 vcc, 0, v143
	s_cbranch_vccz .LBB0_309
	s_nop 0
	v_cndmask_b32_e32 v4, 0, v143, vcc
	v_exp_f32_e64 v6, -v4
	v_add_f32_e32 v183, v183, v4
	v_xor_b32_e32 v2, 0x80000000, v183
	v_pk_add_f32 v[50:51], v[50:51], v[4:5] op_sel_hi:[1,0] neg_lo:[0,1] neg_hi:[0,1]
	v_pk_add_f32 v[66:67], v[66:67], v[4:5] op_sel_hi:[1,0] neg_lo:[0,1] neg_hi:[0,1]
	v_pk_add_f32 v[52:53], v[52:53], v[4:5] op_sel_hi:[1,0] neg_lo:[0,1] neg_hi:[0,1]
	v_pk_add_f32 v[68:69], v[68:69], v[4:5] op_sel_hi:[1,0] neg_lo:[0,1] neg_hi:[0,1]
	v_pk_add_f32 v[54:55], v[54:55], v[4:5] op_sel_hi:[1,0] neg_lo:[0,1] neg_hi:[0,1]
	v_pk_add_f32 v[70:71], v[70:71], v[4:5] op_sel_hi:[1,0] neg_lo:[0,1] neg_hi:[0,1]
	v_pk_add_f32 v[56:57], v[56:57], v[4:5] op_sel_hi:[1,0] neg_lo:[0,1] neg_hi:[0,1]
	v_pk_add_f32 v[72:73], v[72:73], v[4:5] op_sel_hi:[1,0] neg_lo:[0,1] neg_hi:[0,1]
	v_pk_add_f32 v[58:59], v[58:59], v[4:5] op_sel_hi:[1,0] neg_lo:[0,1] neg_hi:[0,1]
	v_pk_add_f32 v[74:75], v[74:75], v[4:5] op_sel_hi:[1,0] neg_lo:[0,1] neg_hi:[0,1]
	v_pk_add_f32 v[60:61], v[60:61], v[4:5] op_sel_hi:[1,0] neg_lo:[0,1] neg_hi:[0,1]
	v_pk_add_f32 v[76:77], v[76:77], v[4:5] op_sel_hi:[1,0] neg_lo:[0,1] neg_hi:[0,1]
	v_pk_add_f32 v[62:63], v[62:63], v[4:5] op_sel_hi:[1,0] neg_lo:[0,1] neg_hi:[0,1]
	v_pk_add_f32 v[78:79], v[78:79], v[4:5] op_sel_hi:[1,0] neg_lo:[0,1] neg_hi:[0,1]
	v_pk_mul_f32 v[48:49], v[48:49], v[6:7] op_sel_hi:[1,0]
	v_pk_mul_f32 v[46:47], v[46:47], v[6:7] op_sel_hi:[1,0]
	v_pk_mul_f32 v[44:45], v[44:45], v[6:7] op_sel_hi:[1,0]
	v_pk_mul_f32 v[42:43], v[42:43], v[6:7] op_sel_hi:[1,0]
	v_pk_mul_f32 v[40:41], v[40:41], v[6:7] op_sel_hi:[1,0]
	v_pk_mul_f32 v[38:39], v[38:39], v[6:7] op_sel_hi:[1,0]
	v_pk_mul_f32 v[36:37], v[36:37], v[6:7] op_sel_hi:[1,0]
	v_pk_mul_f32 v[34:35], v[34:35], v[6:7] op_sel_hi:[1,0]
	v_pk_mul_f32 v[32:33], v[32:33], v[6:7] op_sel_hi:[1,0]
	v_pk_mul_f32 v[30:31], v[30:31], v[6:7] op_sel_hi:[1,0]
	v_pk_mul_f32 v[28:29], v[28:29], v[6:7] op_sel_hi:[1,0]
	v_pk_mul_f32 v[26:27], v[26:27], v[6:7] op_sel_hi:[1,0]
	v_pk_mul_f32 v[24:25], v[24:25], v[6:7] op_sel_hi:[1,0]
	v_pk_mul_f32 v[22:23], v[22:23], v[6:7] op_sel_hi:[1,0]
	v_pk_mul_f32 v[20:21], v[20:21], v[6:7] op_sel_hi:[1,0]
	v_pk_mul_f32 v[18:19], v[18:19], v[6:7] op_sel_hi:[1,0]
	v_pk_add_f32 v[64:65], v[64:65], v[4:5] op_sel_hi:[1,0] neg_lo:[0,1] neg_hi:[0,1]
	v_pk_add_f32 v[80:81], v[80:81], v[4:5] op_sel_hi:[1,0] neg_lo:[0,1] neg_hi:[0,1]
	v_mul_f32_e32 v142, v142, v6
	v_mov_b32_e32 v3, v2
	v_mov_b32_e32 v4, v2
	v_mov_b32_e32 v5, v2
	v_mov_b32_e32 v6, v2
	v_mov_b32_e32 v7, v2
	v_mov_b32_e32 v8, v2
	v_mov_b32_e32 v9, v2
	v_mov_b32_e32 v10, v2
	v_mov_b32_e32 v11, v2
	v_mov_b32_e32 v12, v2
	v_mov_b32_e32 v13, v2
	v_mov_b32_e32 v14, v2
	v_mov_b32_e32 v15, v2
	v_mov_b32_e32 v16, v2
	v_mov_b32_e32 v17, v2
; #define LAS __attribute__((address_space(3)))
; __device__ __forceinline__ unsigned pk2(float lo, float hi) { const f32x2_t v = {lo, hi}; const bf16x2_t b = __builtin_convertvector(v, bf16x2_t); return __builtin_bit_cast(unsigned, b); }
; template <bool NA> ...
;     ...
;             float ls = 0.f;
; #pragma unroll
;             for (int r = 0; r < 16; ++r) { p0[r] = __builtin_amdgcn_exp2f(p0[r]); p1[r] = __builtin_amdgcn_exp2f(p1[r]); ls += p0[r] + p1[r]; }
;             l += ls;
;             bf16x8 pb[4];
;             { u32x4 w;
;               w.x = pk2(p0[0], p0[1]); w.y = pk2(p0[2], p0[3]); w.z = pk2(p0[4], p0[5]); w.w = pk2(p0[6], p0[7]); pb[0] = __builtin_bit_cast(bf16x8, w);
;               w.x = pk2(p0[8], p0[9]); w.y = pk2(p0[10], p0[11]); w.z = pk2(p0[12], p0[13]); w.w = pk2(p0[14], p0[15]); pb[1] = __builtin_bit_cast(bf16x8, w);
;               w.x = pk2(p1[0], p1[1]); w.y = pk2(p1[2], p1[3]); w.z = pk2(p1[4], p1[5]); w.w = pk2(p1[6], p1[7]); pb[2] = __builtin_bit_cast(bf16x8, w);
;               w.x = pk2(p1[8], p1[9]); w.y = pk2(p1[10], p1[11]); w.z = pk2(p1[12], p1[13]); w.w = pk2(p1[14], p1[15]); pb[3] = __builtin_bit_cast(bf16x8, w); }
; #pragma unroll
;             for (int s = 0; s < 4; ++s) {
;                 const bf16x8 vf0 = vfr[2 * s], vf1 = vfr[2 * s + 1];
;                 o0 = __builtin_amdgcn_mfma_f32_32x32x16_bf16(vf0, pb[s], o0, 0, 0, 0);
;                 o1 = __builtin_amdgcn_mfma_f32_32x32x16_bf16(vf1, pb[s], o1, 0, 0, 0);
;             }
;         }
;         if (j + 1 < ntiles) {
;             *(LAS u32x4*)(lds + (cur ^ 1) * KB + srow * 144 + sch * 16) = kreg;
;             LAS unsigned char* vp = lds + VOFF + (cur ^ 1) * VB + srow * 144 + (sch >> 1) * 32 + (sch & 1) * 8;
;             *(LAS u32x2*)vp = (u32x2){vreg.x, vreg.y}; *(LAS u32x2*)(vp + 16) = (u32x2){vreg.z, vreg.w};
;         }
.LBB0_309:
	v_exp_f32_e32 v50, v50
	v_exp_f32_e32 v51, v51
	v_exp_f32_e32 v52, v52
	v_exp_f32_e32 v53, v53
	v_exp_f32_e32 v54, v54
	v_exp_f32_e32 v55, v55
	v_exp_f32_e32 v56, v56
	v_exp_f32_e32 v57, v57
	v_cvt_pk_bf16_f32 v144, v50, v51
	v_cvt_pk_bf16_f32 v145, v52, v53
	v_cvt_pk_bf16_f32 v146, v54, v55
	v_cvt_pk_bf16_f32 v147, v56, v57
	v_exp_f32_e32 v58, v58
	v_exp_f32_e32 v59, v59
	s_waitcnt lgkmcnt(7)
	v_mfma_f32_32x32x16_bf16 v[34:49], v[134:137], v[144:147], v[34:49]
	v_exp_f32_e32 v60, v60
	v_exp_f32_e32 v61, v61
	v_exp_f32_e32 v62, v62
	v_exp_f32_e32 v63, v63
	v_exp_f32_e32 v64, v64
	v_exp_f32_e32 v65, v65
	v_cvt_pk_bf16_f32 v148, v58, v59
	s_waitcnt lgkmcnt(5)
	v_mfma_f32_32x32x16_bf16 v[18:33], v[130:133], v[144:147], v[18:33]
	v_cvt_pk_bf16_f32 v149, v60, v61
	v_cvt_pk_bf16_f32 v150, v62, v63
	v_cvt_pk_bf16_f32 v151, v64, v65
	v_exp_f32_e32 v66, v66
	v_exp_f32_e32 v67, v67
	v_exp_f32_e32 v68, v68
	v_exp_f32_e32 v69, v69
	v_mfma_f32_32x32x16_bf16 v[34:49], v[126:129], v[148:151], v[34:49]
	v_exp_f32_e32 v70, v70
	v_exp_f32_e32 v71, v71
	v_exp_f32_e32 v72, v72
	v_exp_f32_e32 v73, v73
	v_cvt_pk_bf16_f32 v188, v66, v67
	v_cvt_pk_bf16_f32 v189, v68, v69
	v_cvt_pk_bf16_f32 v190, v70, v71
	s_waitcnt lgkmcnt(4)
	v_mfma_f32_32x32x16_bf16 v[18:33], v[122:125], v[148:151], v[18:33]
	v_cvt_pk_bf16_f32 v191, v72, v73
	v_exp_f32_e32 v74, v74
	v_exp_f32_e32 v75, v75
	v_exp_f32_e32 v76, v76
	v_exp_f32_e32 v77, v77
	v_exp_f32_e32 v78, v78
	v_exp_f32_e32 v79, v79
	s_waitcnt lgkmcnt(3)
	v_mfma_f32_32x32x16_bf16 v[34:49], v[118:121], v[188:191], v[34:49]
	v_exp_f32_e32 v80, v80
	v_exp_f32_e32 v81, v81
	v_cvt_pk_bf16_f32 v196, v74, v75
	v_cvt_pk_bf16_f32 v197, v76, v77
	v_cvt_pk_bf16_f32 v198, v78, v79
	v_cvt_pk_bf16_f32 v199, v80, v81
	s_andn2_b64 vcc, exec, s[42:43]
	s_waitcnt lgkmcnt(1)
	v_mfma_f32_32x32x16_bf16 v[18:33], v[114:117], v[188:191], v[18:33]
	v_pk_add_f32 v[50:51], v[50:51], v[66:67]
	v_pk_add_f32 v[52:53], v[52:53], v[68:69]
	v_pk_add_f32 v[54:55], v[54:55], v[70:71]
	v_pk_add_f32 v[56:57], v[56:57], v[72:73]
	v_pk_add_f32 v[58:59], v[58:59], v[74:75]
	v_pk_add_f32 v[60:61], v[60:61], v[76:77]
	v_pk_add_f32 v[62:63], v[62:63], v[78:79]
	v_pk_add_f32 v[64:65], v[64:65], v[80:81]
	v_mfma_f32_32x32x16_bf16 v[34:49], v[90:93], v[196:199], v[34:49]
	v_pk_add_f32 v[50:51], v[50:51], v[52:53]
	v_pk_add_f32 v[54:55], v[54:55], v[56:57]
	v_pk_add_f32 v[58:59], v[58:59], v[60:61]
	v_pk_add_f32 v[62:63], v[62:63], v[64:65]
	v_pk_add_f32 v[50:51], v[50:51], v[54:55]
	v_pk_add_f32 v[58:59], v[58:59], v[62:63]
	v_pk_add_f32 v[50:51], v[50:51], v[58:59]
	v_add_f32_e32 v50, v50, v51
	s_waitcnt lgkmcnt(0)
	v_mfma_f32_32x32x16_bf16 v[18:33], v[94:97], v[196:199], v[18:33]
	s_cbranch_vccnz .LBB0_304
	s_xor_b32 s20, s20, 1
	s_mulk_i32 s20, 0x2400
	v_add_u32_e32 v90, s20, v192
	v_add_u32_e32 v91, s20, v167
	v_add_u32_e32 v90, 0x4800, v90
	s_waitcnt vmcnt(1)
	ds_write_b128 v91, v[82:85]
	s_waitcnt vmcnt(0)
	ds_write2_b64 v90, v[86:87], v[88:89] offset1:2
	s_branch .LBB0_304
